# P4: gate-code loads of mid-K rescale and epilogue hoisted (16 in flight instead of 1), same math
# speedup vs baseline: 1.0067x; 1.0067x over previous
;     static __device__ __forceinline__ float ub(unsigned w, int k) { return (float)((w >> (8 * k)) & 0xffu); }
;     __device__ __forceinline__ void mid(f32x4 (&acc)[2][2][4][2], const Unit& u, int wr, int wc, int fr, int fq) const {
;         unsigned off0 = (unsigned)((u.pm * BM + wr * 64 + fr) * 1024 + u.pn * BM + wc * 32 + 8 * fq);
;         asm volatile("" : "+v"(off0));
; #pragma unroll
;         for (int ai = 0; ai < 2; ++ai)
; #pragma unroll
;             for (int m = 0; m < 4; ++m) { const unsigned off = off0 + (unsigned)((ai * HALF + m * 16) * 1024);
; #pragma unroll
;                 for (int bj = 0; bj < 2; ++bj) { const u32x4 g = *(const u32x4*)(AB + (off + bj * HALF));
;                     acc[ai][bj][m][0] *= (f32x4){ub(g.x, 0) * __builtin_amdgcn_rcpf(ub(g.x, 1)), ub(g.x, 2) * __builtin_amdgcn_rcpf(ub(g.x, 3)), ub(g.y, 0) * __builtin_amdgcn_rcpf(ub(g.y, 1)), ub(g.y, 2) * __builtin_amdgcn_rcpf(ub(g.y, 3))};
;                     acc[ai][bj][m][1] *= (f32x4){ub(g.z, 0) * __builtin_amdgcn_rcpf(ub(g.z, 1)), ub(g.z, 2) * __builtin_amdgcn_rcpf(ub(g.z, 3)), ub(g.w, 0) * __builtin_amdgcn_rcpf(ub(g.w, 1)), ub(g.w, 2) * __builtin_amdgcn_rcpf(ub(g.w, 3))}; } }
;     }
.LBB0_508:
	s_cmpk_lg_i32 s34, 0x400
	s_cbranch_scc1 .LBB0_507
	v_lshlrev_b32_e32 v2, 1, v168
	v_add_u32_e32 v240, 0x8000, v2
	v_add_u32_e32 v241, 0x10000, v2
	v_add_u32_e32 v242, 0x18000, v2
	v_add_u32_e32 v243, 0x40000, v2
	v_add_u32_e32 v244, 0x48000, v2
	v_add_u32_e32 v245, 0x50000, v2
	v_add_u32_e32 v246, 0x58000, v2
	global_load_dwordx4 v[176:179], v2, s[10:11] offset:0
	global_load_dwordx4 v[180:183], v2, s[10:11] offset:256
	global_load_dwordx4 v[184:187], v240, s[10:11] offset:0
	global_load_dwordx4 v[188:191], v240, s[10:11] offset:256
	global_load_dwordx4 v[192:195], v241, s[10:11] offset:0
	global_load_dwordx4 v[196:199], v241, s[10:11] offset:256
	global_load_dwordx4 v[200:203], v242, s[10:11] offset:0
	global_load_dwordx4 v[204:207], v242, s[10:11] offset:256
	global_load_dwordx4 v[208:211], v243, s[10:11] offset:0
	global_load_dwordx4 v[212:215], v243, s[10:11] offset:256
	global_load_dwordx4 v[216:219], v244, s[10:11] offset:0
	global_load_dwordx4 v[220:223], v244, s[10:11] offset:256
	global_load_dwordx4 v[224:227], v245, s[10:11] offset:0
	global_load_dwordx4 v[228:231], v245, s[10:11] offset:256
	global_load_dwordx4 v[232:235], v246, s[10:11] offset:0
	global_load_dwordx4 v[236:239], v246, s[10:11] offset:256
	s_waitcnt vmcnt(15)
	v_cvt_f32_ubyte1_e32 v142, v176
	v_cvt_f32_ubyte3_e32 v143, v176
	v_cvt_f32_ubyte1_e32 v144, v177
	v_cvt_f32_ubyte3_e32 v145, v177
	v_cvt_f32_ubyte1_e32 v146, v178
	v_cvt_f32_ubyte3_e32 v147, v178
	v_cvt_f32_ubyte1_e32 v148, v179
	v_cvt_f32_ubyte3_e32 v149, v179
	v_cvt_f32_ubyte0_e32 v134, v176
	v_cvt_f32_ubyte2_e32 v135, v176
	v_cvt_f32_ubyte0_e32 v136, v177
	v_cvt_f32_ubyte2_e32 v137, v177
	v_cvt_f32_ubyte0_e32 v138, v178
	v_cvt_f32_ubyte2_e32 v139, v178
	v_cvt_f32_ubyte0_e32 v140, v179
	v_cvt_f32_ubyte2_e32 v141, v179
	v_rcp_iflag_f32_e32 v142, v142
	v_rcp_iflag_f32_e32 v143, v143
	v_rcp_iflag_f32_e32 v144, v144
	v_rcp_iflag_f32_e32 v145, v145
	v_rcp_iflag_f32_e32 v146, v146
	v_rcp_iflag_f32_e32 v147, v147
	v_rcp_iflag_f32_e32 v148, v148
	v_rcp_iflag_f32_e32 v149, v149
	v_mul_f32_e32 v134, v134, v142
	v_mul_f32_e32 v135, v135, v143
	v_mul_f32_e32 v136, v136, v144
	v_mul_f32_e32 v137, v137, v145
	v_mul_f32_e32 v138, v138, v146
	v_mul_f32_e32 v139, v139, v147
	v_mul_f32_e32 v140, v140, v148
	v_mul_f32_e32 v141, v141, v149
	v_pk_mul_f32 v[130:131], v[130:131], v[134:135]
	v_pk_mul_f32 v[132:133], v[132:133], v[136:137]
	v_pk_mul_f32 v[126:127], v[126:127], v[138:139]
	v_pk_mul_f32 v[128:129], v[128:129], v[140:141]
	s_waitcnt vmcnt(14)
	v_cvt_f32_ubyte1_e32 v142, v180
	v_cvt_f32_ubyte3_e32 v143, v180
	v_cvt_f32_ubyte1_e32 v144, v181
	v_cvt_f32_ubyte3_e32 v145, v181
	v_cvt_f32_ubyte1_e32 v146, v182
	v_cvt_f32_ubyte3_e32 v147, v182
	v_cvt_f32_ubyte1_e32 v148, v183
	v_cvt_f32_ubyte3_e32 v149, v183
	v_cvt_f32_ubyte0_e32 v134, v180
	v_cvt_f32_ubyte2_e32 v135, v180
	v_cvt_f32_ubyte0_e32 v136, v181
	v_cvt_f32_ubyte2_e32 v137, v181
	v_cvt_f32_ubyte0_e32 v138, v182
	v_cvt_f32_ubyte2_e32 v139, v182
	v_cvt_f32_ubyte0_e32 v140, v183
	v_cvt_f32_ubyte2_e32 v141, v183
	v_rcp_iflag_f32_e32 v142, v142
	v_rcp_iflag_f32_e32 v143, v143
	v_rcp_iflag_f32_e32 v144, v144
	v_rcp_iflag_f32_e32 v145, v145
	v_rcp_iflag_f32_e32 v146, v146
	v_rcp_iflag_f32_e32 v147, v147
	v_rcp_iflag_f32_e32 v148, v148
	v_rcp_iflag_f32_e32 v149, v149
	v_mul_f32_e32 v134, v134, v142
	v_mul_f32_e32 v135, v135, v143
	v_mul_f32_e32 v136, v136, v144
	v_mul_f32_e32 v137, v137, v145
	v_mul_f32_e32 v138, v138, v146
	v_mul_f32_e32 v139, v139, v147
	v_mul_f32_e32 v140, v140, v148
	v_mul_f32_e32 v141, v141, v149
	v_pk_mul_f32 v[122:123], v[122:123], v[134:135]
	v_pk_mul_f32 v[124:125], v[124:125], v[136:137]
	v_pk_mul_f32 v[118:119], v[118:119], v[138:139]
	v_pk_mul_f32 v[120:121], v[120:121], v[140:141]
	s_waitcnt vmcnt(13)
	v_cvt_f32_ubyte1_e32 v142, v184
	v_cvt_f32_ubyte3_e32 v143, v184
	v_cvt_f32_ubyte1_e32 v144, v185
	v_cvt_f32_ubyte3_e32 v145, v185
	v_cvt_f32_ubyte1_e32 v146, v186
	v_cvt_f32_ubyte3_e32 v147, v186
	v_cvt_f32_ubyte1_e32 v148, v187
	v_cvt_f32_ubyte3_e32 v149, v187
	v_cvt_f32_ubyte0_e32 v134, v184
	v_cvt_f32_ubyte2_e32 v135, v184
	v_cvt_f32_ubyte0_e32 v136, v185
	v_cvt_f32_ubyte2_e32 v137, v185
	v_cvt_f32_ubyte0_e32 v138, v186
	v_cvt_f32_ubyte2_e32 v139, v186
	v_cvt_f32_ubyte0_e32 v140, v187
	v_cvt_f32_ubyte2_e32 v141, v187
	v_rcp_iflag_f32_e32 v142, v142
	v_rcp_iflag_f32_e32 v143, v143
	v_rcp_iflag_f32_e32 v144, v144
	v_rcp_iflag_f32_e32 v145, v145
	v_rcp_iflag_f32_e32 v146, v146
	v_rcp_iflag_f32_e32 v147, v147
	v_rcp_iflag_f32_e32 v148, v148
	v_rcp_iflag_f32_e32 v149, v149
	v_mul_f32_e32 v134, v134, v142
	v_mul_f32_e32 v135, v135, v143
	v_mul_f32_e32 v136, v136, v144
	v_mul_f32_e32 v137, v137, v145
	v_mul_f32_e32 v138, v138, v146
	v_mul_f32_e32 v139, v139, v147
	v_mul_f32_e32 v140, v140, v148
	v_mul_f32_e32 v141, v141, v149
	v_pk_mul_f32 v[114:115], v[114:115], v[134:135]
	v_pk_mul_f32 v[116:117], v[116:117], v[136:137]
	v_pk_mul_f32 v[110:111], v[110:111], v[138:139]
	v_pk_mul_f32 v[112:113], v[112:113], v[140:141]
	s_waitcnt vmcnt(12)
;     static __device__ __forceinline__ float ub(unsigned w, int k) { return (float)((w >> (8 * k)) & 0xffu); }
;     __device__ __forceinline__ void mid(f32x4 (&acc)[2][2][4][2], const Unit& u, int wr, int wc, int fr, int fq) const {
;     ...
;             for (int m = 0; m < 4; ++m) { const unsigned off = off0 + (unsigned)((ai * HALF + m * 16) * 1024);
; #pragma unroll
;                 for (int bj = 0; bj < 2; ++bj) { const u32x4 g = *(const u32x4*)(AB + (off + bj * HALF));
;                     acc[ai][bj][m][0] *= (f32x4){ub(g.x, 0) * __builtin_amdgcn_rcpf(ub(g.x, 1)), ub(g.x, 2) * __builtin_amdgcn_rcpf(ub(g.x, 3)), ub(g.y, 0) * __builtin_amdgcn_rcpf(ub(g.y, 1)), ub(g.y, 2) * __builtin_amdgcn_rcpf(ub(g.y, 3))};
;                     acc[ai][bj][m][1] *= (f32x4){ub(g.z, 0) * __builtin_amdgcn_rcpf(ub(g.z, 1)), ub(g.z, 2) * __builtin_amdgcn_rcpf(ub(g.z, 3)), ub(g.w, 0) * __builtin_amdgcn_rcpf(ub(g.w, 1)), ub(g.w, 2) * __builtin_amdgcn_rcpf(ub(g.w, 3))}; } }
	v_cvt_f32_ubyte1_e32 v142, v188
	v_cvt_f32_ubyte3_e32 v143, v188
	v_cvt_f32_ubyte1_e32 v144, v189
	v_cvt_f32_ubyte3_e32 v145, v189
	v_cvt_f32_ubyte1_e32 v146, v190
	v_cvt_f32_ubyte3_e32 v147, v190
	v_cvt_f32_ubyte1_e32 v148, v191
	v_cvt_f32_ubyte3_e32 v149, v191
	v_cvt_f32_ubyte0_e32 v134, v188
	v_cvt_f32_ubyte2_e32 v135, v188
	v_cvt_f32_ubyte0_e32 v136, v189
	v_cvt_f32_ubyte2_e32 v137, v189
	v_cvt_f32_ubyte0_e32 v138, v190
	v_cvt_f32_ubyte2_e32 v139, v190
	v_cvt_f32_ubyte0_e32 v140, v191
	v_cvt_f32_ubyte2_e32 v141, v191
	v_rcp_iflag_f32_e32 v142, v142
	v_rcp_iflag_f32_e32 v143, v143
	v_rcp_iflag_f32_e32 v144, v144
	v_rcp_iflag_f32_e32 v145, v145
	v_rcp_iflag_f32_e32 v146, v146
	v_rcp_iflag_f32_e32 v147, v147
	v_rcp_iflag_f32_e32 v148, v148
	v_rcp_iflag_f32_e32 v149, v149
	v_mul_f32_e32 v134, v134, v142
	v_mul_f32_e32 v135, v135, v143
	v_mul_f32_e32 v136, v136, v144
	v_mul_f32_e32 v137, v137, v145
	v_mul_f32_e32 v138, v138, v146
	v_mul_f32_e32 v139, v139, v147
	v_mul_f32_e32 v140, v140, v148
	v_mul_f32_e32 v141, v141, v149
	v_pk_mul_f32 v[106:107], v[106:107], v[134:135]
	v_pk_mul_f32 v[108:109], v[108:109], v[136:137]
	v_pk_mul_f32 v[102:103], v[102:103], v[138:139]
	v_pk_mul_f32 v[104:105], v[104:105], v[140:141]
	s_waitcnt vmcnt(11)
	v_cvt_f32_ubyte1_e32 v142, v192
	v_cvt_f32_ubyte3_e32 v143, v192
	v_cvt_f32_ubyte1_e32 v144, v193
	v_cvt_f32_ubyte3_e32 v145, v193
	v_cvt_f32_ubyte1_e32 v146, v194
	v_cvt_f32_ubyte3_e32 v147, v194
	v_cvt_f32_ubyte1_e32 v148, v195
	v_cvt_f32_ubyte3_e32 v149, v195
	v_cvt_f32_ubyte0_e32 v134, v192
	v_cvt_f32_ubyte2_e32 v135, v192
	v_cvt_f32_ubyte0_e32 v136, v193
	v_cvt_f32_ubyte2_e32 v137, v193
	v_cvt_f32_ubyte0_e32 v138, v194
	v_cvt_f32_ubyte2_e32 v139, v194
	v_cvt_f32_ubyte0_e32 v140, v195
	v_cvt_f32_ubyte2_e32 v141, v195
	v_rcp_iflag_f32_e32 v142, v142
	v_rcp_iflag_f32_e32 v143, v143
	v_rcp_iflag_f32_e32 v144, v144
	v_rcp_iflag_f32_e32 v145, v145
	v_rcp_iflag_f32_e32 v146, v146
	v_rcp_iflag_f32_e32 v147, v147
	v_rcp_iflag_f32_e32 v148, v148
	v_rcp_iflag_f32_e32 v149, v149
	v_mul_f32_e32 v134, v134, v142
	v_mul_f32_e32 v135, v135, v143
	v_mul_f32_e32 v136, v136, v144
	v_mul_f32_e32 v137, v137, v145
	v_mul_f32_e32 v138, v138, v146
	v_mul_f32_e32 v139, v139, v147
	v_mul_f32_e32 v140, v140, v148
	v_mul_f32_e32 v141, v141, v149
	v_pk_mul_f32 v[98:99], v[98:99], v[134:135]
	v_pk_mul_f32 v[100:101], v[100:101], v[136:137]
	v_pk_mul_f32 v[94:95], v[94:95], v[138:139]
	v_pk_mul_f32 v[96:97], v[96:97], v[140:141]
	s_waitcnt vmcnt(10)
	v_cvt_f32_ubyte1_e32 v142, v196
	v_cvt_f32_ubyte3_e32 v143, v196
	v_cvt_f32_ubyte1_e32 v144, v197
	v_cvt_f32_ubyte3_e32 v145, v197
	v_cvt_f32_ubyte1_e32 v146, v198
	v_cvt_f32_ubyte3_e32 v147, v198
	v_cvt_f32_ubyte1_e32 v148, v199
	v_cvt_f32_ubyte3_e32 v149, v199
	v_cvt_f32_ubyte0_e32 v134, v196
	v_cvt_f32_ubyte2_e32 v135, v196
	v_cvt_f32_ubyte0_e32 v136, v197
	v_cvt_f32_ubyte2_e32 v137, v197
	v_cvt_f32_ubyte0_e32 v138, v198
	v_cvt_f32_ubyte2_e32 v139, v198
	v_cvt_f32_ubyte0_e32 v140, v199
	v_cvt_f32_ubyte2_e32 v141, v199
	v_rcp_iflag_f32_e32 v142, v142
	v_rcp_iflag_f32_e32 v143, v143
	v_rcp_iflag_f32_e32 v144, v144
	v_rcp_iflag_f32_e32 v145, v145
	v_rcp_iflag_f32_e32 v146, v146
	v_rcp_iflag_f32_e32 v147, v147
	v_rcp_iflag_f32_e32 v148, v148
	v_rcp_iflag_f32_e32 v149, v149
	v_mul_f32_e32 v134, v134, v142
	v_mul_f32_e32 v135, v135, v143
	v_mul_f32_e32 v136, v136, v144
	v_mul_f32_e32 v137, v137, v145
	v_mul_f32_e32 v138, v138, v146
	v_mul_f32_e32 v139, v139, v147
	v_mul_f32_e32 v140, v140, v148
	v_mul_f32_e32 v141, v141, v149
	v_pk_mul_f32 v[90:91], v[90:91], v[134:135]
	v_pk_mul_f32 v[92:93], v[92:93], v[136:137]
	v_pk_mul_f32 v[86:87], v[86:87], v[138:139]
	v_pk_mul_f32 v[88:89], v[88:89], v[140:141]
	s_waitcnt vmcnt(9)
	v_cvt_f32_ubyte1_e32 v142, v200
	v_cvt_f32_ubyte3_e32 v143, v200
	v_cvt_f32_ubyte1_e32 v144, v201
	v_cvt_f32_ubyte3_e32 v145, v201
	v_cvt_f32_ubyte1_e32 v146, v202
	v_cvt_f32_ubyte3_e32 v147, v202
	v_cvt_f32_ubyte1_e32 v148, v203
	v_cvt_f32_ubyte3_e32 v149, v203
	v_cvt_f32_ubyte0_e32 v134, v200
	v_cvt_f32_ubyte2_e32 v135, v200
	v_cvt_f32_ubyte0_e32 v136, v201
	v_cvt_f32_ubyte2_e32 v137, v201
	v_cvt_f32_ubyte0_e32 v138, v202
	v_cvt_f32_ubyte2_e32 v139, v202
	v_cvt_f32_ubyte0_e32 v140, v203
	v_cvt_f32_ubyte2_e32 v141, v203
	v_rcp_iflag_f32_e32 v142, v142
	v_rcp_iflag_f32_e32 v143, v143
	v_rcp_iflag_f32_e32 v144, v144
	v_rcp_iflag_f32_e32 v145, v145
	v_rcp_iflag_f32_e32 v146, v146
	v_rcp_iflag_f32_e32 v147, v147
	v_rcp_iflag_f32_e32 v148, v148
	v_rcp_iflag_f32_e32 v149, v149
	v_mul_f32_e32 v134, v134, v142
	v_mul_f32_e32 v135, v135, v143
	v_mul_f32_e32 v136, v136, v144
	v_mul_f32_e32 v137, v137, v145
	v_mul_f32_e32 v138, v138, v146
	v_mul_f32_e32 v139, v139, v147
	v_mul_f32_e32 v140, v140, v148
	v_mul_f32_e32 v141, v141, v149
	v_pk_mul_f32 v[82:83], v[82:83], v[134:135]
	v_pk_mul_f32 v[84:85], v[84:85], v[136:137]
	v_pk_mul_f32 v[78:79], v[78:79], v[138:139]
	v_pk_mul_f32 v[80:81], v[80:81], v[140:141]
	s_waitcnt vmcnt(8)
	v_cvt_f32_ubyte1_e32 v142, v204
	v_cvt_f32_ubyte3_e32 v143, v204
	v_cvt_f32_ubyte1_e32 v144, v205
	v_cvt_f32_ubyte3_e32 v145, v205
	v_cvt_f32_ubyte1_e32 v146, v206
	v_cvt_f32_ubyte3_e32 v147, v206
	v_cvt_f32_ubyte1_e32 v148, v207
	v_cvt_f32_ubyte3_e32 v149, v207
	v_cvt_f32_ubyte0_e32 v134, v204
	v_cvt_f32_ubyte2_e32 v135, v204
	v_cvt_f32_ubyte0_e32 v136, v205
	v_cvt_f32_ubyte2_e32 v137, v205
	v_cvt_f32_ubyte0_e32 v138, v206
	v_cvt_f32_ubyte2_e32 v139, v206
	v_cvt_f32_ubyte0_e32 v140, v207
	v_cvt_f32_ubyte2_e32 v141, v207
	v_rcp_iflag_f32_e32 v142, v142
	v_rcp_iflag_f32_e32 v143, v143
	v_rcp_iflag_f32_e32 v144, v144
	v_rcp_iflag_f32_e32 v145, v145
	v_rcp_iflag_f32_e32 v146, v146
	v_rcp_iflag_f32_e32 v147, v147
	v_rcp_iflag_f32_e32 v148, v148
	v_rcp_iflag_f32_e32 v149, v149
	v_mul_f32_e32 v134, v134, v142
	v_mul_f32_e32 v135, v135, v143
	v_mul_f32_e32 v136, v136, v144
	v_mul_f32_e32 v137, v137, v145
	v_mul_f32_e32 v138, v138, v146
	v_mul_f32_e32 v139, v139, v147
	v_mul_f32_e32 v140, v140, v148
	v_mul_f32_e32 v141, v141, v149
	v_pk_mul_f32 v[74:75], v[74:75], v[134:135]
	v_pk_mul_f32 v[76:77], v[76:77], v[136:137]
	v_pk_mul_f32 v[70:71], v[70:71], v[138:139]
	v_pk_mul_f32 v[72:73], v[72:73], v[140:141]
	s_waitcnt vmcnt(7)
;     static __device__ __forceinline__ float ub(unsigned w, int k) { return (float)((w >> (8 * k)) & 0xffu); }
;     __device__ __forceinline__ void mid(f32x4 (&acc)[2][2][4][2], const Unit& u, int wr, int wc, int fr, int fq) const {
;     ...
;             for (int m = 0; m < 4; ++m) { const unsigned off = off0 + (unsigned)((ai * HALF + m * 16) * 1024);
; #pragma unroll
;                 for (int bj = 0; bj < 2; ++bj) { const u32x4 g = *(const u32x4*)(AB + (off + bj * HALF));
;                     acc[ai][bj][m][0] *= (f32x4){ub(g.x, 0) * __builtin_amdgcn_rcpf(ub(g.x, 1)), ub(g.x, 2) * __builtin_amdgcn_rcpf(ub(g.x, 3)), ub(g.y, 0) * __builtin_amdgcn_rcpf(ub(g.y, 1)), ub(g.y, 2) * __builtin_amdgcn_rcpf(ub(g.y, 3))};
;                     acc[ai][bj][m][1] *= (f32x4){ub(g.z, 0) * __builtin_amdgcn_rcpf(ub(g.z, 1)), ub(g.z, 2) * __builtin_amdgcn_rcpf(ub(g.z, 3)), ub(g.w, 0) * __builtin_amdgcn_rcpf(ub(g.w, 1)), ub(g.w, 2) * __builtin_amdgcn_rcpf(ub(g.w, 3))}; } }
	v_cvt_f32_ubyte1_e32 v142, v208
	v_cvt_f32_ubyte3_e32 v143, v208
	v_cvt_f32_ubyte1_e32 v144, v209
	v_cvt_f32_ubyte3_e32 v145, v209
	v_cvt_f32_ubyte1_e32 v146, v210
	v_cvt_f32_ubyte3_e32 v147, v210
	v_cvt_f32_ubyte1_e32 v148, v211
	v_cvt_f32_ubyte3_e32 v149, v211
	v_cvt_f32_ubyte0_e32 v134, v208
	v_cvt_f32_ubyte2_e32 v135, v208
	v_cvt_f32_ubyte0_e32 v136, v209
	v_cvt_f32_ubyte2_e32 v137, v209
	v_cvt_f32_ubyte0_e32 v138, v210
	v_cvt_f32_ubyte2_e32 v139, v210
	v_cvt_f32_ubyte0_e32 v140, v211
	v_cvt_f32_ubyte2_e32 v141, v211
	v_rcp_iflag_f32_e32 v142, v142
	v_rcp_iflag_f32_e32 v143, v143
	v_rcp_iflag_f32_e32 v144, v144
	v_rcp_iflag_f32_e32 v145, v145
	v_rcp_iflag_f32_e32 v146, v146
	v_rcp_iflag_f32_e32 v147, v147
	v_rcp_iflag_f32_e32 v148, v148
	v_rcp_iflag_f32_e32 v149, v149
	v_mul_f32_e32 v134, v134, v142
	v_mul_f32_e32 v135, v135, v143
	v_mul_f32_e32 v136, v136, v144
	v_mul_f32_e32 v137, v137, v145
	v_mul_f32_e32 v138, v138, v146
	v_mul_f32_e32 v139, v139, v147
	v_mul_f32_e32 v140, v140, v148
	v_mul_f32_e32 v141, v141, v149
	v_pk_mul_f32 v[66:67], v[66:67], v[134:135]
	v_pk_mul_f32 v[68:69], v[68:69], v[136:137]
	v_pk_mul_f32 v[62:63], v[62:63], v[138:139]
	v_pk_mul_f32 v[64:65], v[64:65], v[140:141]
	s_waitcnt vmcnt(6)
	v_cvt_f32_ubyte1_e32 v142, v212
	v_cvt_f32_ubyte3_e32 v143, v212
	v_cvt_f32_ubyte1_e32 v144, v213
	v_cvt_f32_ubyte3_e32 v145, v213
	v_cvt_f32_ubyte1_e32 v146, v214
	v_cvt_f32_ubyte3_e32 v147, v214
	v_cvt_f32_ubyte1_e32 v148, v215
	v_cvt_f32_ubyte3_e32 v149, v215
	v_cvt_f32_ubyte0_e32 v134, v212
	v_cvt_f32_ubyte2_e32 v135, v212
	v_cvt_f32_ubyte0_e32 v136, v213
	v_cvt_f32_ubyte2_e32 v137, v213
	v_cvt_f32_ubyte0_e32 v138, v214
	v_cvt_f32_ubyte2_e32 v139, v214
	v_cvt_f32_ubyte0_e32 v140, v215
	v_cvt_f32_ubyte2_e32 v141, v215
	v_rcp_iflag_f32_e32 v142, v142
	v_rcp_iflag_f32_e32 v143, v143
	v_rcp_iflag_f32_e32 v144, v144
	v_rcp_iflag_f32_e32 v145, v145
	v_rcp_iflag_f32_e32 v146, v146
	v_rcp_iflag_f32_e32 v147, v147
	v_rcp_iflag_f32_e32 v148, v148
	v_rcp_iflag_f32_e32 v149, v149
	v_mul_f32_e32 v134, v134, v142
	v_mul_f32_e32 v135, v135, v143
	v_mul_f32_e32 v136, v136, v144
	v_mul_f32_e32 v137, v137, v145
	v_mul_f32_e32 v138, v138, v146
	v_mul_f32_e32 v139, v139, v147
	v_mul_f32_e32 v140, v140, v148
	v_mul_f32_e32 v141, v141, v149
	v_pk_mul_f32 v[58:59], v[58:59], v[134:135]
	v_pk_mul_f32 v[60:61], v[60:61], v[136:137]
	v_pk_mul_f32 v[54:55], v[54:55], v[138:139]
	v_pk_mul_f32 v[56:57], v[56:57], v[140:141]
	s_waitcnt vmcnt(5)
	v_cvt_f32_ubyte1_e32 v142, v216
	v_cvt_f32_ubyte3_e32 v143, v216
	v_cvt_f32_ubyte1_e32 v144, v217
	v_cvt_f32_ubyte3_e32 v145, v217
	v_cvt_f32_ubyte1_e32 v146, v218
	v_cvt_f32_ubyte3_e32 v147, v218
	v_cvt_f32_ubyte1_e32 v148, v219
	v_cvt_f32_ubyte3_e32 v149, v219
	v_cvt_f32_ubyte0_e32 v134, v216
	v_cvt_f32_ubyte2_e32 v135, v216
	v_cvt_f32_ubyte0_e32 v136, v217
	v_cvt_f32_ubyte2_e32 v137, v217
	v_cvt_f32_ubyte0_e32 v138, v218
	v_cvt_f32_ubyte2_e32 v139, v218
	v_cvt_f32_ubyte0_e32 v140, v219
	v_cvt_f32_ubyte2_e32 v141, v219
	v_rcp_iflag_f32_e32 v142, v142
	v_rcp_iflag_f32_e32 v143, v143
	v_rcp_iflag_f32_e32 v144, v144
	v_rcp_iflag_f32_e32 v145, v145
	v_rcp_iflag_f32_e32 v146, v146
	v_rcp_iflag_f32_e32 v147, v147
	v_rcp_iflag_f32_e32 v148, v148
	v_rcp_iflag_f32_e32 v149, v149
	v_mul_f32_e32 v134, v134, v142
	v_mul_f32_e32 v135, v135, v143
	v_mul_f32_e32 v136, v136, v144
	v_mul_f32_e32 v137, v137, v145
	v_mul_f32_e32 v138, v138, v146
	v_mul_f32_e32 v139, v139, v147
	v_mul_f32_e32 v140, v140, v148
	v_mul_f32_e32 v141, v141, v149
	v_pk_mul_f32 v[50:51], v[50:51], v[134:135]
	v_pk_mul_f32 v[52:53], v[52:53], v[136:137]
	v_pk_mul_f32 v[46:47], v[46:47], v[138:139]
	v_pk_mul_f32 v[48:49], v[48:49], v[140:141]
	s_waitcnt vmcnt(4)
	v_cvt_f32_ubyte1_e32 v142, v220
	v_cvt_f32_ubyte3_e32 v143, v220
	v_cvt_f32_ubyte1_e32 v144, v221
	v_cvt_f32_ubyte3_e32 v145, v221
	v_cvt_f32_ubyte1_e32 v146, v222
	v_cvt_f32_ubyte3_e32 v147, v222
	v_cvt_f32_ubyte1_e32 v148, v223
	v_cvt_f32_ubyte3_e32 v149, v223
	v_cvt_f32_ubyte0_e32 v134, v220
	v_cvt_f32_ubyte2_e32 v135, v220
	v_cvt_f32_ubyte0_e32 v136, v221
	v_cvt_f32_ubyte2_e32 v137, v221
	v_cvt_f32_ubyte0_e32 v138, v222
	v_cvt_f32_ubyte2_e32 v139, v222
	v_cvt_f32_ubyte0_e32 v140, v223
	v_cvt_f32_ubyte2_e32 v141, v223
	v_rcp_iflag_f32_e32 v142, v142
	v_rcp_iflag_f32_e32 v143, v143
	v_rcp_iflag_f32_e32 v144, v144
	v_rcp_iflag_f32_e32 v145, v145
	v_rcp_iflag_f32_e32 v146, v146
	v_rcp_iflag_f32_e32 v147, v147
	v_rcp_iflag_f32_e32 v148, v148
	v_rcp_iflag_f32_e32 v149, v149
	v_mul_f32_e32 v134, v134, v142
	v_mul_f32_e32 v135, v135, v143
	v_mul_f32_e32 v136, v136, v144
	v_mul_f32_e32 v137, v137, v145
	v_mul_f32_e32 v138, v138, v146
	v_mul_f32_e32 v139, v139, v147
	v_mul_f32_e32 v140, v140, v148
	v_mul_f32_e32 v141, v141, v149
	v_pk_mul_f32 v[42:43], v[42:43], v[134:135]
	v_pk_mul_f32 v[44:45], v[44:45], v[136:137]
	v_pk_mul_f32 v[38:39], v[38:39], v[138:139]
	v_pk_mul_f32 v[40:41], v[40:41], v[140:141]
	s_waitcnt vmcnt(3)
;     static __device__ __forceinline__ float ub(unsigned w, int k) { return (float)((w >> (8 * k)) & 0xffu); }
;     __device__ __forceinline__ void mid(f32x4 (&acc)[2][2][4][2], const Unit& u, int wr, int wc, int fr, int fq) const {
;     ...
;             for (int m = 0; m < 4; ++m) { const unsigned off = off0 + (unsigned)((ai * HALF + m * 16) * 1024);
; #pragma unroll
;                 for (int bj = 0; bj < 2; ++bj) { const u32x4 g = *(const u32x4*)(AB + (off + bj * HALF));
;                     acc[ai][bj][m][0] *= (f32x4){ub(g.x, 0) * __builtin_amdgcn_rcpf(ub(g.x, 1)), ub(g.x, 2) * __builtin_amdgcn_rcpf(ub(g.x, 3)), ub(g.y, 0) * __builtin_amdgcn_rcpf(ub(g.y, 1)), ub(g.y, 2) * __builtin_amdgcn_rcpf(ub(g.y, 3))};
;                     acc[ai][bj][m][1] *= (f32x4){ub(g.z, 0) * __builtin_amdgcn_rcpf(ub(g.z, 1)), ub(g.z, 2) * __builtin_amdgcn_rcpf(ub(g.z, 3)), ub(g.w, 0) * __builtin_amdgcn_rcpf(ub(g.w, 1)), ub(g.w, 2) * __builtin_amdgcn_rcpf(ub(g.w, 3))}; } }
	v_cvt_f32_ubyte1_e32 v142, v224
	v_cvt_f32_ubyte3_e32 v143, v224
	v_cvt_f32_ubyte1_e32 v144, v225
	v_cvt_f32_ubyte3_e32 v145, v225
	v_cvt_f32_ubyte1_e32 v146, v226
	v_cvt_f32_ubyte3_e32 v147, v226
	v_cvt_f32_ubyte1_e32 v148, v227
	v_cvt_f32_ubyte3_e32 v149, v227
	v_cvt_f32_ubyte0_e32 v134, v224
	v_cvt_f32_ubyte2_e32 v135, v224
	v_cvt_f32_ubyte0_e32 v136, v225
	v_cvt_f32_ubyte2_e32 v137, v225
	v_cvt_f32_ubyte0_e32 v138, v226
	v_cvt_f32_ubyte2_e32 v139, v226
	v_cvt_f32_ubyte0_e32 v140, v227
	v_cvt_f32_ubyte2_e32 v141, v227
	v_rcp_iflag_f32_e32 v142, v142
	v_rcp_iflag_f32_e32 v143, v143
	v_rcp_iflag_f32_e32 v144, v144
	v_rcp_iflag_f32_e32 v145, v145
	v_rcp_iflag_f32_e32 v146, v146
	v_rcp_iflag_f32_e32 v147, v147
	v_rcp_iflag_f32_e32 v148, v148
	v_rcp_iflag_f32_e32 v149, v149
	v_mul_f32_e32 v134, v134, v142
	v_mul_f32_e32 v135, v135, v143
	v_mul_f32_e32 v136, v136, v144
	v_mul_f32_e32 v137, v137, v145
	v_mul_f32_e32 v138, v138, v146
	v_mul_f32_e32 v139, v139, v147
	v_mul_f32_e32 v140, v140, v148
	v_mul_f32_e32 v141, v141, v149
	v_pk_mul_f32 v[34:35], v[34:35], v[134:135]
	v_pk_mul_f32 v[36:37], v[36:37], v[136:137]
	v_pk_mul_f32 v[30:31], v[30:31], v[138:139]
	v_pk_mul_f32 v[32:33], v[32:33], v[140:141]
	s_waitcnt vmcnt(2)
	v_cvt_f32_ubyte1_e32 v142, v228
	v_cvt_f32_ubyte3_e32 v143, v228
	v_cvt_f32_ubyte1_e32 v144, v229
	v_cvt_f32_ubyte3_e32 v145, v229
	v_cvt_f32_ubyte1_e32 v146, v230
	v_cvt_f32_ubyte3_e32 v147, v230
	v_cvt_f32_ubyte1_e32 v148, v231
	v_cvt_f32_ubyte3_e32 v149, v231
	v_cvt_f32_ubyte0_e32 v134, v228
	v_cvt_f32_ubyte2_e32 v135, v228
	v_cvt_f32_ubyte0_e32 v136, v229
	v_cvt_f32_ubyte2_e32 v137, v229
	v_cvt_f32_ubyte0_e32 v138, v230
	v_cvt_f32_ubyte2_e32 v139, v230
	v_cvt_f32_ubyte0_e32 v140, v231
	v_cvt_f32_ubyte2_e32 v141, v231
	v_rcp_iflag_f32_e32 v142, v142
	v_rcp_iflag_f32_e32 v143, v143
	v_rcp_iflag_f32_e32 v144, v144
	v_rcp_iflag_f32_e32 v145, v145
	v_rcp_iflag_f32_e32 v146, v146
	v_rcp_iflag_f32_e32 v147, v147
	v_rcp_iflag_f32_e32 v148, v148
	v_rcp_iflag_f32_e32 v149, v149
	v_mul_f32_e32 v134, v134, v142
	v_mul_f32_e32 v135, v135, v143
	v_mul_f32_e32 v136, v136, v144
	v_mul_f32_e32 v137, v137, v145
	v_mul_f32_e32 v138, v138, v146
	v_mul_f32_e32 v139, v139, v147
	v_mul_f32_e32 v140, v140, v148
	v_mul_f32_e32 v141, v141, v149
	v_pk_mul_f32 v[26:27], v[26:27], v[134:135]
	v_pk_mul_f32 v[28:29], v[28:29], v[136:137]
	v_pk_mul_f32 v[22:23], v[22:23], v[138:139]
	v_pk_mul_f32 v[24:25], v[24:25], v[140:141]
	s_waitcnt vmcnt(1)
	v_cvt_f32_ubyte1_e32 v142, v232
	v_cvt_f32_ubyte3_e32 v143, v232
	v_cvt_f32_ubyte1_e32 v144, v233
	v_cvt_f32_ubyte3_e32 v145, v233
	v_cvt_f32_ubyte1_e32 v146, v234
	v_cvt_f32_ubyte3_e32 v147, v234
	v_cvt_f32_ubyte1_e32 v148, v235
	v_cvt_f32_ubyte3_e32 v149, v235
	v_cvt_f32_ubyte0_e32 v134, v232
	v_cvt_f32_ubyte2_e32 v135, v232
	v_cvt_f32_ubyte0_e32 v136, v233
	v_cvt_f32_ubyte2_e32 v137, v233
	v_cvt_f32_ubyte0_e32 v138, v234
	v_cvt_f32_ubyte2_e32 v139, v234
	v_cvt_f32_ubyte0_e32 v140, v235
	v_cvt_f32_ubyte2_e32 v141, v235
	v_rcp_iflag_f32_e32 v142, v142
	v_rcp_iflag_f32_e32 v143, v143
	v_rcp_iflag_f32_e32 v144, v144
	v_rcp_iflag_f32_e32 v145, v145
	v_rcp_iflag_f32_e32 v146, v146
	v_rcp_iflag_f32_e32 v147, v147
	v_rcp_iflag_f32_e32 v148, v148
	v_rcp_iflag_f32_e32 v149, v149
	v_mul_f32_e32 v134, v134, v142
	v_mul_f32_e32 v135, v135, v143
	v_mul_f32_e32 v136, v136, v144
	v_mul_f32_e32 v137, v137, v145
	v_mul_f32_e32 v138, v138, v146
	v_mul_f32_e32 v139, v139, v147
	v_mul_f32_e32 v140, v140, v148
	v_mul_f32_e32 v141, v141, v149
	v_pk_mul_f32 v[18:19], v[18:19], v[134:135]
	v_pk_mul_f32 v[20:21], v[20:21], v[136:137]
	v_pk_mul_f32 v[14:15], v[14:15], v[138:139]
	v_pk_mul_f32 v[16:17], v[16:17], v[140:141]
	s_waitcnt vmcnt(0)
	v_cvt_f32_ubyte1_e32 v142, v236
	v_cvt_f32_ubyte3_e32 v143, v236
	v_cvt_f32_ubyte1_e32 v144, v237
	v_cvt_f32_ubyte3_e32 v145, v237
	v_cvt_f32_ubyte1_e32 v146, v238
	v_cvt_f32_ubyte3_e32 v147, v238
	v_cvt_f32_ubyte1_e32 v148, v239
	v_cvt_f32_ubyte3_e32 v149, v239
	v_cvt_f32_ubyte0_e32 v134, v236
	v_cvt_f32_ubyte2_e32 v135, v236
	v_cvt_f32_ubyte0_e32 v136, v237
	v_cvt_f32_ubyte2_e32 v137, v237
	v_cvt_f32_ubyte0_e32 v138, v238
	v_cvt_f32_ubyte2_e32 v139, v238
	v_cvt_f32_ubyte0_e32 v140, v239
	v_cvt_f32_ubyte2_e32 v141, v239
	v_rcp_iflag_f32_e32 v142, v142
	v_rcp_iflag_f32_e32 v143, v143
	v_rcp_iflag_f32_e32 v144, v144
	v_rcp_iflag_f32_e32 v145, v145
	v_rcp_iflag_f32_e32 v146, v146
	v_rcp_iflag_f32_e32 v147, v147
	v_rcp_iflag_f32_e32 v148, v148
	v_rcp_iflag_f32_e32 v149, v149
	v_mul_f32_e32 v134, v134, v142
	v_mul_f32_e32 v135, v135, v143
	v_mul_f32_e32 v136, v136, v144
	v_mul_f32_e32 v137, v137, v145
	v_mul_f32_e32 v138, v138, v146
	v_mul_f32_e32 v139, v139, v147
	v_mul_f32_e32 v140, v140, v148
	v_mul_f32_e32 v141, v141, v149
	v_pk_mul_f32 v[10:11], v[10:11], v[134:135]
	v_pk_mul_f32 v[12:13], v[12:13], v[136:137]
	v_pk_mul_f32 v[6:7], v[6:7], v[138:139]
	v_pk_mul_f32 v[8:9], v[8:9], v[140:141]
	s_branch .LBB0_507

; __device__ __forceinline__ unsigned cvt_pk_bf16(float lo, float hi) { unsigned r; asm volatile("v_cvt_pk_bf16_f32 %0, %1, %2" : "=v"(r) : "v"(lo), "v"(hi)); return r; }
;     static __device__ __forceinline__ float ub(unsigned w, int k) { return (float)((w >> (8 * k)) & 0xffu); }
;     __device__ __forceinline__ void operator()(const f32x4 (&acc)[2][2][4][2], const Unit& u, int wr, int wc, int fr, int fq) const {
;         unsigned off0 = (unsigned)((u.pm * BM + wr * 64 + fr) * 1024 + u.pn * BM + wc * 32 + 8 * fq); const float s = 1.0f / 255.0f;
;         asm volatile("" : "+v"(off0));
; #pragma unroll
;         for (int ai = 0; ai < 2; ++ai)
; #pragma unroll
;             for (int m = 0; m < 4; ++m) { const unsigned off = off0 + (unsigned)((ai * HALF + m * 16) * 1024);
; #pragma unroll
;                 for (int bj = 0; bj < 2; ++bj) { const u32x4 g = *(const u32x4*)(AB + (off + bj * HALF)); const f32x4 v0 = acc[ai][bj][m][0] * s, v1 = acc[ai][bj][m][1] * s;
;                     u32x4 w; w.x = cvt_pk_bf16(v0[0] * ub(g.x, 1), v0[1] * ub(g.x, 3)); w.y = cvt_pk_bf16(v0[2] * ub(g.y, 1), v0[3] * ub(g.y, 3));
;                     w.z = cvt_pk_bf16(v1[0] * ub(g.z, 1), v1[1] * ub(g.z, 3)); w.w = cvt_pk_bf16(v1[2] * ub(g.w, 1), v1[3] * ub(g.w, 3));
;                     *(u32x4*)((unsigned char*)MG + 2u * (off + bj * HALF)) = w; } }
;     }
.LBB0_512:
	v_lshlrev_b32_e32 v2, 1, v168
	v_add_u32_e32 v240, 0x8000, v2
	v_add_u32_e32 v241, 0x10000, v2
	v_add_u32_e32 v242, 0x18000, v2
	v_add_u32_e32 v243, 0x40000, v2
	v_add_u32_e32 v244, 0x48000, v2
	v_add_u32_e32 v245, 0x50000, v2
	v_add_u32_e32 v246, 0x58000, v2
	global_load_dwordx4 v[176:179], v2, s[10:11] offset:0
	global_load_dwordx4 v[180:183], v2, s[10:11] offset:256
	global_load_dwordx4 v[184:187], v240, s[10:11] offset:0
	global_load_dwordx4 v[188:191], v240, s[10:11] offset:256
	global_load_dwordx4 v[192:195], v241, s[10:11] offset:0
	global_load_dwordx4 v[196:199], v241, s[10:11] offset:256
	global_load_dwordx4 v[200:203], v242, s[10:11] offset:0
	global_load_dwordx4 v[204:207], v242, s[10:11] offset:256
	global_load_dwordx4 v[208:211], v243, s[10:11] offset:0
	global_load_dwordx4 v[212:215], v243, s[10:11] offset:256
	global_load_dwordx4 v[216:219], v244, s[10:11] offset:0
	global_load_dwordx4 v[220:223], v244, s[10:11] offset:256
	global_load_dwordx4 v[224:227], v245, s[10:11] offset:0
	global_load_dwordx4 v[228:231], v245, s[10:11] offset:256
	global_load_dwordx4 v[232:235], v246, s[10:11] offset:0
	global_load_dwordx4 v[236:239], v246, s[10:11] offset:256
	s_waitcnt vmcnt(15)
	v_pk_mul_f32 v[130:131], v[130:131], s[16:17] op_sel_hi:[1,0]
	v_pk_mul_f32 v[132:133], v[132:133], s[16:17] op_sel_hi:[1,0]
	v_pk_mul_f32 v[126:127], v[126:127], s[16:17] op_sel_hi:[1,0]
	v_pk_mul_f32 v[128:129], v[128:129], s[16:17] op_sel_hi:[1,0]
	v_cvt_f32_ubyte1_e32 v134, v176
	v_cvt_f32_ubyte3_e32 v135, v176
	v_cvt_f32_ubyte1_e32 v136, v177
	v_cvt_f32_ubyte3_e32 v137, v177
	v_cvt_f32_ubyte1_e32 v138, v178
	v_cvt_f32_ubyte3_e32 v139, v178
	v_cvt_f32_ubyte1_e32 v140, v179
	v_cvt_f32_ubyte3_e32 v141, v179
	v_mul_f32_e32 v130, v130, v134
	v_mul_f32_e32 v131, v131, v135
	v_mul_f32_e32 v132, v132, v136
	v_mul_f32_e32 v133, v133, v137
	v_mul_f32_e32 v126, v126, v138
	v_mul_f32_e32 v127, v127, v139
	v_mul_f32_e32 v128, v128, v140
	v_mul_f32_e32 v129, v129, v141
	v_cvt_pk_bf16_f32 v176, v130, v131
	v_cvt_pk_bf16_f32 v177, v132, v133
	v_cvt_pk_bf16_f32 v178, v126, v127
	v_cvt_pk_bf16_f32 v179, v128, v129
	global_store_dwordx4 v2, v[176:179], s[8:9] offset:0
	s_waitcnt vmcnt(15)
	v_pk_mul_f32 v[122:123], v[122:123], s[16:17] op_sel_hi:[1,0]
	v_pk_mul_f32 v[124:125], v[124:125], s[16:17] op_sel_hi:[1,0]
	v_pk_mul_f32 v[118:119], v[118:119], s[16:17] op_sel_hi:[1,0]
	v_pk_mul_f32 v[120:121], v[120:121], s[16:17] op_sel_hi:[1,0]
	v_cvt_f32_ubyte1_e32 v134, v180
	v_cvt_f32_ubyte3_e32 v135, v180
	v_cvt_f32_ubyte1_e32 v136, v181
	v_cvt_f32_ubyte3_e32 v137, v181
	v_cvt_f32_ubyte1_e32 v138, v182
	v_cvt_f32_ubyte3_e32 v139, v182
	v_cvt_f32_ubyte1_e32 v140, v183
	v_cvt_f32_ubyte3_e32 v141, v183
	v_mul_f32_e32 v122, v122, v134
	v_mul_f32_e32 v123, v123, v135
	v_mul_f32_e32 v124, v124, v136
	v_mul_f32_e32 v125, v125, v137
	v_mul_f32_e32 v118, v118, v138
	v_mul_f32_e32 v119, v119, v139
	v_mul_f32_e32 v120, v120, v140
	v_mul_f32_e32 v121, v121, v141
	v_cvt_pk_bf16_f32 v180, v122, v123
	v_cvt_pk_bf16_f32 v181, v124, v125
	v_cvt_pk_bf16_f32 v182, v118, v119
	v_cvt_pk_bf16_f32 v183, v120, v121
	global_store_dwordx4 v2, v[180:183], s[8:9] offset:256
	s_waitcnt vmcnt(15)
	v_pk_mul_f32 v[114:115], v[114:115], s[16:17] op_sel_hi:[1,0]
	v_pk_mul_f32 v[116:117], v[116:117], s[16:17] op_sel_hi:[1,0]
	v_pk_mul_f32 v[110:111], v[110:111], s[16:17] op_sel_hi:[1,0]
	v_pk_mul_f32 v[112:113], v[112:113], s[16:17] op_sel_hi:[1,0]
	v_cvt_f32_ubyte1_e32 v134, v184
	v_cvt_f32_ubyte3_e32 v135, v184
	v_cvt_f32_ubyte1_e32 v136, v185
	v_cvt_f32_ubyte3_e32 v137, v185
	v_cvt_f32_ubyte1_e32 v138, v186
	v_cvt_f32_ubyte3_e32 v139, v186
	v_cvt_f32_ubyte1_e32 v140, v187
	v_cvt_f32_ubyte3_e32 v141, v187
	v_mul_f32_e32 v114, v114, v134
	v_mul_f32_e32 v115, v115, v135
	v_mul_f32_e32 v116, v116, v136
	v_mul_f32_e32 v117, v117, v137
	v_mul_f32_e32 v110, v110, v138
	v_mul_f32_e32 v111, v111, v139
	v_mul_f32_e32 v112, v112, v140
	v_mul_f32_e32 v113, v113, v141
	v_cvt_pk_bf16_f32 v184, v114, v115
	v_cvt_pk_bf16_f32 v185, v116, v117
	v_cvt_pk_bf16_f32 v186, v110, v111
	v_cvt_pk_bf16_f32 v187, v112, v113
	global_store_dwordx4 v240, v[184:187], s[8:9] offset:0
	s_waitcnt vmcnt(15)
	v_pk_mul_f32 v[106:107], v[106:107], s[16:17] op_sel_hi:[1,0]
	v_pk_mul_f32 v[108:109], v[108:109], s[16:17] op_sel_hi:[1,0]
	v_pk_mul_f32 v[102:103], v[102:103], s[16:17] op_sel_hi:[1,0]
	v_pk_mul_f32 v[104:105], v[104:105], s[16:17] op_sel_hi:[1,0]
	v_cvt_f32_ubyte1_e32 v134, v188
	v_cvt_f32_ubyte3_e32 v135, v188
	v_cvt_f32_ubyte1_e32 v136, v189
	v_cvt_f32_ubyte3_e32 v137, v189
	v_cvt_f32_ubyte1_e32 v138, v190
	v_cvt_f32_ubyte3_e32 v139, v190
	v_cvt_f32_ubyte1_e32 v140, v191
	v_cvt_f32_ubyte3_e32 v141, v191
	v_mul_f32_e32 v106, v106, v134
	v_mul_f32_e32 v107, v107, v135
	v_mul_f32_e32 v108, v108, v136
	v_mul_f32_e32 v109, v109, v137
	v_mul_f32_e32 v102, v102, v138
	v_mul_f32_e32 v103, v103, v139
	v_mul_f32_e32 v104, v104, v140
	v_mul_f32_e32 v105, v105, v141
	v_cvt_pk_bf16_f32 v188, v106, v107
	v_cvt_pk_bf16_f32 v189, v108, v109
	v_cvt_pk_bf16_f32 v190, v102, v103
	v_cvt_pk_bf16_f32 v191, v104, v105
	global_store_dwordx4 v240, v[188:191], s[8:9] offset:256
	s_waitcnt vmcnt(15)
; __device__ __forceinline__ unsigned cvt_pk_bf16(float lo, float hi) { unsigned r; asm volatile("v_cvt_pk_bf16_f32 %0, %1, %2" : "=v"(r) : "v"(lo), "v"(hi)); return r; }
;     static __device__ __forceinline__ float ub(unsigned w, int k) { return (float)((w >> (8 * k)) & 0xffu); }
;     __device__ __forceinline__ void operator()(const f32x4 (&acc)[2][2][4][2], const Unit& u, int wr, int wc, int fr, int fq) const {
;     ...
;             for (int m = 0; m < 4; ++m) { const unsigned off = off0 + (unsigned)((ai * HALF + m * 16) * 1024);
; #pragma unroll
;                 for (int bj = 0; bj < 2; ++bj) { const u32x4 g = *(const u32x4*)(AB + (off + bj * HALF)); const f32x4 v0 = acc[ai][bj][m][0] * s, v1 = acc[ai][bj][m][1] * s;
;                     u32x4 w; w.x = cvt_pk_bf16(v0[0] * ub(g.x, 1), v0[1] * ub(g.x, 3)); w.y = cvt_pk_bf16(v0[2] * ub(g.y, 1), v0[3] * ub(g.y, 3));
;                     w.z = cvt_pk_bf16(v1[0] * ub(g.z, 1), v1[1] * ub(g.z, 3)); w.w = cvt_pk_bf16(v1[2] * ub(g.w, 1), v1[3] * ub(g.w, 3));
;                     *(u32x4*)((unsigned char*)MG + 2u * (off + bj * HALF)) = w; } }
	v_pk_mul_f32 v[98:99], v[98:99], s[16:17] op_sel_hi:[1,0]
	v_pk_mul_f32 v[100:101], v[100:101], s[16:17] op_sel_hi:[1,0]
	v_pk_mul_f32 v[94:95], v[94:95], s[16:17] op_sel_hi:[1,0]
	v_pk_mul_f32 v[96:97], v[96:97], s[16:17] op_sel_hi:[1,0]
	v_cvt_f32_ubyte1_e32 v134, v192
	v_cvt_f32_ubyte3_e32 v135, v192
	v_cvt_f32_ubyte1_e32 v136, v193
	v_cvt_f32_ubyte3_e32 v137, v193
	v_cvt_f32_ubyte1_e32 v138, v194
	v_cvt_f32_ubyte3_e32 v139, v194
	v_cvt_f32_ubyte1_e32 v140, v195
	v_cvt_f32_ubyte3_e32 v141, v195
	v_mul_f32_e32 v98, v98, v134
	v_mul_f32_e32 v99, v99, v135
	v_mul_f32_e32 v100, v100, v136
	v_mul_f32_e32 v101, v101, v137
	v_mul_f32_e32 v94, v94, v138
	v_mul_f32_e32 v95, v95, v139
	v_mul_f32_e32 v96, v96, v140
	v_mul_f32_e32 v97, v97, v141
	v_cvt_pk_bf16_f32 v192, v98, v99
	v_cvt_pk_bf16_f32 v193, v100, v101
	v_cvt_pk_bf16_f32 v194, v94, v95
	v_cvt_pk_bf16_f32 v195, v96, v97
	global_store_dwordx4 v241, v[192:195], s[8:9] offset:0
	s_waitcnt vmcnt(15)
	v_pk_mul_f32 v[90:91], v[90:91], s[16:17] op_sel_hi:[1,0]
	v_pk_mul_f32 v[92:93], v[92:93], s[16:17] op_sel_hi:[1,0]
	v_pk_mul_f32 v[86:87], v[86:87], s[16:17] op_sel_hi:[1,0]
	v_pk_mul_f32 v[88:89], v[88:89], s[16:17] op_sel_hi:[1,0]
	v_cvt_f32_ubyte1_e32 v134, v196
	v_cvt_f32_ubyte3_e32 v135, v196
	v_cvt_f32_ubyte1_e32 v136, v197
	v_cvt_f32_ubyte3_e32 v137, v197
	v_cvt_f32_ubyte1_e32 v138, v198
	v_cvt_f32_ubyte3_e32 v139, v198
	v_cvt_f32_ubyte1_e32 v140, v199
	v_cvt_f32_ubyte3_e32 v141, v199
	v_mul_f32_e32 v90, v90, v134
	v_mul_f32_e32 v91, v91, v135
	v_mul_f32_e32 v92, v92, v136
	v_mul_f32_e32 v93, v93, v137
	v_mul_f32_e32 v86, v86, v138
	v_mul_f32_e32 v87, v87, v139
	v_mul_f32_e32 v88, v88, v140
	v_mul_f32_e32 v89, v89, v141
	v_cvt_pk_bf16_f32 v196, v90, v91
	v_cvt_pk_bf16_f32 v197, v92, v93
	v_cvt_pk_bf16_f32 v198, v86, v87
	v_cvt_pk_bf16_f32 v199, v88, v89
	global_store_dwordx4 v241, v[196:199], s[8:9] offset:256
	s_waitcnt vmcnt(15)
	v_pk_mul_f32 v[82:83], v[82:83], s[16:17] op_sel_hi:[1,0]
	v_pk_mul_f32 v[84:85], v[84:85], s[16:17] op_sel_hi:[1,0]
	v_pk_mul_f32 v[78:79], v[78:79], s[16:17] op_sel_hi:[1,0]
	v_pk_mul_f32 v[80:81], v[80:81], s[16:17] op_sel_hi:[1,0]
	v_cvt_f32_ubyte1_e32 v134, v200
	v_cvt_f32_ubyte3_e32 v135, v200
	v_cvt_f32_ubyte1_e32 v136, v201
	v_cvt_f32_ubyte3_e32 v137, v201
	v_cvt_f32_ubyte1_e32 v138, v202
	v_cvt_f32_ubyte3_e32 v139, v202
	v_cvt_f32_ubyte1_e32 v140, v203
	v_cvt_f32_ubyte3_e32 v141, v203
	v_mul_f32_e32 v82, v82, v134
	v_mul_f32_e32 v83, v83, v135
	v_mul_f32_e32 v84, v84, v136
	v_mul_f32_e32 v85, v85, v137
	v_mul_f32_e32 v78, v78, v138
	v_mul_f32_e32 v79, v79, v139
	v_mul_f32_e32 v80, v80, v140
	v_mul_f32_e32 v81, v81, v141
	v_cvt_pk_bf16_f32 v200, v82, v83
	v_cvt_pk_bf16_f32 v201, v84, v85
	v_cvt_pk_bf16_f32 v202, v78, v79
	v_cvt_pk_bf16_f32 v203, v80, v81
	global_store_dwordx4 v242, v[200:203], s[8:9] offset:0
	s_waitcnt vmcnt(15)
	v_pk_mul_f32 v[74:75], v[74:75], s[16:17] op_sel_hi:[1,0]
	v_pk_mul_f32 v[76:77], v[76:77], s[16:17] op_sel_hi:[1,0]
	v_pk_mul_f32 v[70:71], v[70:71], s[16:17] op_sel_hi:[1,0]
	v_pk_mul_f32 v[72:73], v[72:73], s[16:17] op_sel_hi:[1,0]
	v_cvt_f32_ubyte1_e32 v134, v204
	v_cvt_f32_ubyte3_e32 v135, v204
	v_cvt_f32_ubyte1_e32 v136, v205
	v_cvt_f32_ubyte3_e32 v137, v205
	v_cvt_f32_ubyte1_e32 v138, v206
	v_cvt_f32_ubyte3_e32 v139, v206
	v_cvt_f32_ubyte1_e32 v140, v207
	v_cvt_f32_ubyte3_e32 v141, v207
	v_mul_f32_e32 v74, v74, v134
	v_mul_f32_e32 v75, v75, v135
	v_mul_f32_e32 v76, v76, v136
	v_mul_f32_e32 v77, v77, v137
	v_mul_f32_e32 v70, v70, v138
	v_mul_f32_e32 v71, v71, v139
	v_mul_f32_e32 v72, v72, v140
	v_mul_f32_e32 v73, v73, v141
	v_cvt_pk_bf16_f32 v204, v74, v75
	v_cvt_pk_bf16_f32 v205, v76, v77
	v_cvt_pk_bf16_f32 v206, v70, v71
	v_cvt_pk_bf16_f32 v207, v72, v73
	global_store_dwordx4 v242, v[204:207], s[8:9] offset:256
	s_waitcnt vmcnt(15)
	v_pk_mul_f32 v[66:67], v[66:67], s[16:17] op_sel_hi:[1,0]
	v_pk_mul_f32 v[68:69], v[68:69], s[16:17] op_sel_hi:[1,0]
	v_pk_mul_f32 v[62:63], v[62:63], s[16:17] op_sel_hi:[1,0]
	v_pk_mul_f32 v[64:65], v[64:65], s[16:17] op_sel_hi:[1,0]
	v_cvt_f32_ubyte1_e32 v134, v208
	v_cvt_f32_ubyte3_e32 v135, v208
	v_cvt_f32_ubyte1_e32 v136, v209
	v_cvt_f32_ubyte3_e32 v137, v209
	v_cvt_f32_ubyte1_e32 v138, v210
	v_cvt_f32_ubyte3_e32 v139, v210
	v_cvt_f32_ubyte1_e32 v140, v211
	v_cvt_f32_ubyte3_e32 v141, v211
	v_mul_f32_e32 v66, v66, v134
	v_mul_f32_e32 v67, v67, v135
	v_mul_f32_e32 v68, v68, v136
	v_mul_f32_e32 v69, v69, v137
	v_mul_f32_e32 v62, v62, v138
	v_mul_f32_e32 v63, v63, v139
	v_mul_f32_e32 v64, v64, v140
	v_mul_f32_e32 v65, v65, v141
	v_cvt_pk_bf16_f32 v208, v66, v67
	v_cvt_pk_bf16_f32 v209, v68, v69
	v_cvt_pk_bf16_f32 v210, v62, v63
	v_cvt_pk_bf16_f32 v211, v64, v65
	global_store_dwordx4 v243, v[208:211], s[8:9] offset:0
	s_waitcnt vmcnt(15)
	v_pk_mul_f32 v[58:59], v[58:59], s[16:17] op_sel_hi:[1,0]
	v_pk_mul_f32 v[60:61], v[60:61], s[16:17] op_sel_hi:[1,0]
	v_pk_mul_f32 v[54:55], v[54:55], s[16:17] op_sel_hi:[1,0]
	v_pk_mul_f32 v[56:57], v[56:57], s[16:17] op_sel_hi:[1,0]
	v_cvt_f32_ubyte1_e32 v134, v212
	v_cvt_f32_ubyte3_e32 v135, v212
	v_cvt_f32_ubyte1_e32 v136, v213
	v_cvt_f32_ubyte3_e32 v137, v213
	v_cvt_f32_ubyte1_e32 v138, v214
	v_cvt_f32_ubyte3_e32 v139, v214
	v_cvt_f32_ubyte1_e32 v140, v215
	v_cvt_f32_ubyte3_e32 v141, v215
	v_mul_f32_e32 v58, v58, v134
	v_mul_f32_e32 v59, v59, v135
	v_mul_f32_e32 v60, v60, v136
	v_mul_f32_e32 v61, v61, v137
	v_mul_f32_e32 v54, v54, v138
	v_mul_f32_e32 v55, v55, v139
	v_mul_f32_e32 v56, v56, v140
	v_mul_f32_e32 v57, v57, v141
	v_cvt_pk_bf16_f32 v212, v58, v59
	v_cvt_pk_bf16_f32 v213, v60, v61
	v_cvt_pk_bf16_f32 v214, v54, v55
	v_cvt_pk_bf16_f32 v215, v56, v57
	global_store_dwordx4 v243, v[212:215], s[8:9] offset:256
	s_waitcnt vmcnt(15)
; __device__ __forceinline__ unsigned cvt_pk_bf16(float lo, float hi) { unsigned r; asm volatile("v_cvt_pk_bf16_f32 %0, %1, %2" : "=v"(r) : "v"(lo), "v"(hi)); return r; }
;     static __device__ __forceinline__ float ub(unsigned w, int k) { return (float)((w >> (8 * k)) & 0xffu); }
; #define PG8_BAR __builtin_amdgcn_s_barrier()
;     __device__ __forceinline__ void operator()(const f32x4 (&acc)[2][2][4][2], const Unit& u, int wr, int wc, int fr, int fq) const {
;     ...
;             for (int m = 0; m < 4; ++m) { const unsigned off = off0 + (unsigned)((ai * HALF + m * 16) * 1024);
; #pragma unroll
;                 for (int bj = 0; bj < 2; ++bj) { const u32x4 g = *(const u32x4*)(AB + (off + bj * HALF)); const f32x4 v0 = acc[ai][bj][m][0] * s, v1 = acc[ai][bj][m][1] * s;
;                     u32x4 w; w.x = cvt_pk_bf16(v0[0] * ub(g.x, 1), v0[1] * ub(g.x, 3)); w.y = cvt_pk_bf16(v0[2] * ub(g.y, 1), v0[3] * ub(g.y, 3));
;                     w.z = cvt_pk_bf16(v1[0] * ub(g.z, 1), v1[1] * ub(g.z, 3)); w.w = cvt_pk_bf16(v1[2] * ub(g.w, 1), v1[3] * ub(g.w, 3));
;                     *(u32x4*)((unsigned char*)MG + 2u * (off + bj * HALF)) = w; } }
; template <class Epi, class Sched, bool ALIGN_EPI = false, bool SP2 = false>
; __device__ __forceinline__ void gemm_phase(PG8_LAS unsigned char* lds, const Gemm g, const Sched& S, const Epi& E) {
;     ...
;         if (!has_next) break;
; #pragma unroll
;         for (int a = 0; a < 2; ++a)
; #pragma unroll
;             for (int b = 0; b < 2; ++b)
; #pragma unroll
;                 for (int m = 0; m < 4; ++m)
; #pragma unroll
;                     for (int n = 0; n < 2; ++n) acc[a][b][m][n] = (f32x4){0.f, 0.f, 0.f, 0.f};
;         cur = nxt; cA = nA; cB = nB; ++ui;
;         if constexpr (ALIGN_EPI) { if (wr == 1) PG8_BAR; }
	v_pk_mul_f32 v[50:51], v[50:51], s[16:17] op_sel_hi:[1,0]
	v_pk_mul_f32 v[52:53], v[52:53], s[16:17] op_sel_hi:[1,0]
	v_pk_mul_f32 v[46:47], v[46:47], s[16:17] op_sel_hi:[1,0]
	v_pk_mul_f32 v[48:49], v[48:49], s[16:17] op_sel_hi:[1,0]
	v_cvt_f32_ubyte1_e32 v134, v216
	v_cvt_f32_ubyte3_e32 v135, v216
	v_cvt_f32_ubyte1_e32 v136, v217
	v_cvt_f32_ubyte3_e32 v137, v217
	v_cvt_f32_ubyte1_e32 v138, v218
	v_cvt_f32_ubyte3_e32 v139, v218
	v_cvt_f32_ubyte1_e32 v140, v219
	v_cvt_f32_ubyte3_e32 v141, v219
	v_mul_f32_e32 v50, v50, v134
	v_mul_f32_e32 v51, v51, v135
	v_mul_f32_e32 v52, v52, v136
	v_mul_f32_e32 v53, v53, v137
	v_mul_f32_e32 v46, v46, v138
	v_mul_f32_e32 v47, v47, v139
	v_mul_f32_e32 v48, v48, v140
	v_mul_f32_e32 v49, v49, v141
	v_cvt_pk_bf16_f32 v216, v50, v51
	v_cvt_pk_bf16_f32 v217, v52, v53
	v_cvt_pk_bf16_f32 v218, v46, v47
	v_cvt_pk_bf16_f32 v219, v48, v49
	global_store_dwordx4 v244, v[216:219], s[8:9] offset:0
	s_waitcnt vmcnt(15)
	v_pk_mul_f32 v[42:43], v[42:43], s[16:17] op_sel_hi:[1,0]
	v_pk_mul_f32 v[44:45], v[44:45], s[16:17] op_sel_hi:[1,0]
	v_pk_mul_f32 v[38:39], v[38:39], s[16:17] op_sel_hi:[1,0]
	v_pk_mul_f32 v[40:41], v[40:41], s[16:17] op_sel_hi:[1,0]
	v_cvt_f32_ubyte1_e32 v134, v220
	v_cvt_f32_ubyte3_e32 v135, v220
	v_cvt_f32_ubyte1_e32 v136, v221
	v_cvt_f32_ubyte3_e32 v137, v221
	v_cvt_f32_ubyte1_e32 v138, v222
	v_cvt_f32_ubyte3_e32 v139, v222
	v_cvt_f32_ubyte1_e32 v140, v223
	v_cvt_f32_ubyte3_e32 v141, v223
	v_mul_f32_e32 v42, v42, v134
	v_mul_f32_e32 v43, v43, v135
	v_mul_f32_e32 v44, v44, v136
	v_mul_f32_e32 v45, v45, v137
	v_mul_f32_e32 v38, v38, v138
	v_mul_f32_e32 v39, v39, v139
	v_mul_f32_e32 v40, v40, v140
	v_mul_f32_e32 v41, v41, v141
	v_cvt_pk_bf16_f32 v220, v42, v43
	v_cvt_pk_bf16_f32 v221, v44, v45
	v_cvt_pk_bf16_f32 v222, v38, v39
	v_cvt_pk_bf16_f32 v223, v40, v41
	global_store_dwordx4 v244, v[220:223], s[8:9] offset:256
	s_waitcnt vmcnt(15)
	v_pk_mul_f32 v[34:35], v[34:35], s[16:17] op_sel_hi:[1,0]
	v_pk_mul_f32 v[36:37], v[36:37], s[16:17] op_sel_hi:[1,0]
	v_pk_mul_f32 v[30:31], v[30:31], s[16:17] op_sel_hi:[1,0]
	v_pk_mul_f32 v[32:33], v[32:33], s[16:17] op_sel_hi:[1,0]
	v_cvt_f32_ubyte1_e32 v134, v224
	v_cvt_f32_ubyte3_e32 v135, v224
	v_cvt_f32_ubyte1_e32 v136, v225
	v_cvt_f32_ubyte3_e32 v137, v225
	v_cvt_f32_ubyte1_e32 v138, v226
	v_cvt_f32_ubyte3_e32 v139, v226
	v_cvt_f32_ubyte1_e32 v140, v227
	v_cvt_f32_ubyte3_e32 v141, v227
	v_mul_f32_e32 v34, v34, v134
	v_mul_f32_e32 v35, v35, v135
	v_mul_f32_e32 v36, v36, v136
	v_mul_f32_e32 v37, v37, v137
	v_mul_f32_e32 v30, v30, v138
	v_mul_f32_e32 v31, v31, v139
	v_mul_f32_e32 v32, v32, v140
	v_mul_f32_e32 v33, v33, v141
	v_cvt_pk_bf16_f32 v224, v34, v35
	v_cvt_pk_bf16_f32 v225, v36, v37
	v_cvt_pk_bf16_f32 v226, v30, v31
	v_cvt_pk_bf16_f32 v227, v32, v33
	global_store_dwordx4 v245, v[224:227], s[8:9] offset:0
	s_waitcnt vmcnt(15)
	v_pk_mul_f32 v[26:27], v[26:27], s[16:17] op_sel_hi:[1,0]
	v_pk_mul_f32 v[28:29], v[28:29], s[16:17] op_sel_hi:[1,0]
	v_pk_mul_f32 v[22:23], v[22:23], s[16:17] op_sel_hi:[1,0]
	v_pk_mul_f32 v[24:25], v[24:25], s[16:17] op_sel_hi:[1,0]
	v_cvt_f32_ubyte1_e32 v134, v228
	v_cvt_f32_ubyte3_e32 v135, v228
	v_cvt_f32_ubyte1_e32 v136, v229
	v_cvt_f32_ubyte3_e32 v137, v229
	v_cvt_f32_ubyte1_e32 v138, v230
	v_cvt_f32_ubyte3_e32 v139, v230
	v_cvt_f32_ubyte1_e32 v140, v231
	v_cvt_f32_ubyte3_e32 v141, v231
	v_mul_f32_e32 v26, v26, v134
	v_mul_f32_e32 v27, v27, v135
	v_mul_f32_e32 v28, v28, v136
	v_mul_f32_e32 v29, v29, v137
	v_mul_f32_e32 v22, v22, v138
	v_mul_f32_e32 v23, v23, v139
	v_mul_f32_e32 v24, v24, v140
	v_mul_f32_e32 v25, v25, v141
	v_cvt_pk_bf16_f32 v228, v26, v27
	v_cvt_pk_bf16_f32 v229, v28, v29
	v_cvt_pk_bf16_f32 v230, v22, v23
	v_cvt_pk_bf16_f32 v231, v24, v25
	global_store_dwordx4 v245, v[228:231], s[8:9] offset:256
	s_waitcnt vmcnt(15)
	v_pk_mul_f32 v[18:19], v[18:19], s[16:17] op_sel_hi:[1,0]
	v_pk_mul_f32 v[20:21], v[20:21], s[16:17] op_sel_hi:[1,0]
	v_pk_mul_f32 v[14:15], v[14:15], s[16:17] op_sel_hi:[1,0]
	v_pk_mul_f32 v[16:17], v[16:17], s[16:17] op_sel_hi:[1,0]
	v_cvt_f32_ubyte1_e32 v134, v232
	v_cvt_f32_ubyte3_e32 v135, v232
	v_cvt_f32_ubyte1_e32 v136, v233
	v_cvt_f32_ubyte3_e32 v137, v233
	v_cvt_f32_ubyte1_e32 v138, v234
	v_cvt_f32_ubyte3_e32 v139, v234
	v_cvt_f32_ubyte1_e32 v140, v235
	v_cvt_f32_ubyte3_e32 v141, v235
	v_mul_f32_e32 v18, v18, v134
	v_mul_f32_e32 v19, v19, v135
	v_mul_f32_e32 v20, v20, v136
	v_mul_f32_e32 v21, v21, v137
	v_mul_f32_e32 v14, v14, v138
	v_mul_f32_e32 v15, v15, v139
	v_mul_f32_e32 v16, v16, v140
	v_mul_f32_e32 v17, v17, v141
	v_cvt_pk_bf16_f32 v232, v18, v19
	v_cvt_pk_bf16_f32 v233, v20, v21
	v_cvt_pk_bf16_f32 v234, v14, v15
	v_cvt_pk_bf16_f32 v235, v16, v17
	global_store_dwordx4 v246, v[232:235], s[8:9] offset:0
	s_waitcnt vmcnt(15)
	v_pk_mul_f32 v[10:11], v[10:11], s[16:17] op_sel_hi:[1,0]
	v_pk_mul_f32 v[12:13], v[12:13], s[16:17] op_sel_hi:[1,0]
	v_pk_mul_f32 v[6:7], v[6:7], s[16:17] op_sel_hi:[1,0]
	v_pk_mul_f32 v[8:9], v[8:9], s[16:17] op_sel_hi:[1,0]
	v_cvt_f32_ubyte1_e32 v134, v236
	v_cvt_f32_ubyte3_e32 v135, v236
	v_cvt_f32_ubyte1_e32 v136, v237
	v_cvt_f32_ubyte3_e32 v137, v237
	v_cvt_f32_ubyte1_e32 v138, v238
	v_cvt_f32_ubyte3_e32 v139, v238
	v_cvt_f32_ubyte1_e32 v140, v239
	v_cvt_f32_ubyte3_e32 v141, v239
	v_mul_f32_e32 v10, v10, v134
	v_mul_f32_e32 v11, v11, v135
	v_mul_f32_e32 v12, v12, v136
	v_mul_f32_e32 v13, v13, v137
	v_mul_f32_e32 v6, v6, v138
	v_mul_f32_e32 v7, v7, v139
	v_mul_f32_e32 v8, v8, v140
	v_mul_f32_e32 v9, v9, v141
	v_cvt_pk_bf16_f32 v236, v10, v11
	v_cvt_pk_bf16_f32 v237, v12, v13
	v_cvt_pk_bf16_f32 v238, v6, v7
	v_cvt_pk_bf16_f32 v239, v8, v9
	global_store_dwordx4 v246, v[236:239], s[8:9] offset:256
	s_andn2_b64 vcc, exec, s[4:5]
	s_mov_b64 s[4:5], -1
	s_cbranch_vccnz .LBB0_499
	s_andn2_b64 vcc, exec, s[6:7]
	s_cbranch_vccnz .LBB0_498
	s_barrier
	s_branch .LBB0_498
